# k/v-cache bf16 conversion rewritten as straight-line code with scalar-loaded pointers and all loads in flight
# speedup vs baseline: 1.0021x; 1.0021x over previous
.LBB0_421:
	s_or_b64 exec, exec, s[10:11]
	s_load_dwordx4 s[12:15], s[8:9], 0x10
	s_load_dwordx2 s[4:5], s[8:9], 0xa8
	s_lshl_b32 s20, s6, 23
	v_readlane_b32 s10, v253, 0
	s_nop 0
	v_lshl_add_u32 v0, s10, 9, v224
	v_lshlrev_b32_e32 v1, 5, v0
	v_lshlrev_b32_e32 v2, 4, v0
	s_waitcnt lgkmcnt(0)
	s_add_u32 s12, s12, s20
	s_addc_u32 s13, s13, 0
	s_add_u32 s14, s14, s20
	s_addc_u32 s15, s15, 0
	s_add_u32 s18, s12, 0x400000
	s_addc_u32 s19, s13, 0
	s_add_u32 s38, s14, 0x400000
	s_addc_u32 s39, s15, 0
	global_load_dwordx4 v[8:11], v1, s[12:13] nt
	global_load_dwordx4 v[12:15], v1, s[12:13] offset:16 nt
	global_load_dwordx4 v[16:19], v1, s[18:19] nt
	global_load_dwordx4 v[20:23], v1, s[18:19] offset:16 nt
	global_load_dwordx4 v[24:27], v1, s[14:15] nt
	global_load_dwordx4 v[28:31], v1, s[14:15] offset:16 nt
	global_load_dwordx4 v[32:35], v1, s[38:39] nt
	global_load_dwordx4 v[36:39], v1, s[38:39] offset:16 nt
	s_add_u32 s12, s4, 0xf400000
	s_addc_u32 s13, s5, 0
	s_add_u32 s18, s12, 0x200000
	s_addc_u32 s19, s13, 0
	s_add_u32 s14, s4, 0xf800000
	s_addc_u32 s15, s5, 0
	s_add_u32 s38, s14, 0x200000
	s_addc_u32 s39, s15, 0
	s_waitcnt vmcnt(6)
	v_cvt_pk_bf16_f32 v40, v8, v9
	v_cvt_pk_bf16_f32 v41, v10, v11
	v_cvt_pk_bf16_f32 v42, v12, v13
	v_cvt_pk_bf16_f32 v43, v14, v15
	global_store_dwordx4 v2, v[40:43], s[12:13]
	s_waitcnt vmcnt(5)
	v_cvt_pk_bf16_f32 v44, v16, v17
	v_cvt_pk_bf16_f32 v45, v18, v19
	v_cvt_pk_bf16_f32 v46, v20, v21
	v_cvt_pk_bf16_f32 v47, v22, v23
	global_store_dwordx4 v2, v[44:47], s[18:19]
	s_waitcnt vmcnt(4)
	v_cvt_pk_bf16_f32 v48, v24, v25
	v_cvt_pk_bf16_f32 v49, v26, v27
	v_cvt_pk_bf16_f32 v50, v28, v29
	v_cvt_pk_bf16_f32 v51, v30, v31
	global_store_dwordx4 v2, v[48:51], s[14:15]
	s_waitcnt vmcnt(3)
	v_cvt_pk_bf16_f32 v52, v32, v33
	v_cvt_pk_bf16_f32 v53, v34, v35
	v_cvt_pk_bf16_f32 v54, v36, v37
	v_cvt_pk_bf16_f32 v55, v38, v39
	global_store_dwordx4 v2, v[52:55], s[38:39]
.LBB0_436:
	s_mov_b64 exec, -1
	s_barrier
